# in-proj head-path epilogue: 8 ssq loads hoisted, second rope pair issued with the first into own registers (1 round trip per row block instead of 3), on top of hg_out prefetch
# speedup vs baseline: 1.0035x; 1.0035x over previous
.LBB0_199:
	v_ashrrev_i32_e32 v173, 31, v172
	v_lshl_add_u64 v[174:175], v[172:173], 2, s[46:47]
	global_load_dword v210, v[174:175], off
	global_load_dword v211, v[174:175], off offset:64
	global_load_dword v212, v[174:175], off offset:128
	global_load_dword v213, v[174:175], off offset:192
	global_load_dword v214, v[174:175], off offset:512
	global_load_dword v215, v[174:175], off offset:576
	global_load_dword v216, v[174:175], off offset:640
	global_load_dword v217, v[174:175], off offset:704
	v_lshlrev_b32_e32 v132, 2, v158
	global_load_dwordx4 v[144:147], v132, s[24:25]
	global_load_dwordx4 v[140:143], v132, s[24:25] offset:64
	global_load_dwordx4 v[136:139], v132, s[24:25] offset:128
	s_nop 0
	global_load_dwordx4 v[132:135], v132, s[24:25] offset:192
	s_cmp_lt_i32 s55, 10
	s_cselect_b64 s[66:67], -1, 0
	s_bfe_u32 s24, s26, 0x80006
	s_mov_b32 s65, s64
	s_cmp_gt_i32 s55, 9
	s_waitcnt vmcnt(0)
	v_fmamk_f32 v148, v210, 0x3a800000, v202
	v_rsq_f32_e32 v148, v148
	s_nop 0
	v_pk_mul_f32 v[182:183], v[130:131], v[148:149] op_sel_hi:[1,0]
	v_pk_mul_f32 v[184:185], v[128:129], v[148:149] op_sel_hi:[1,0]
	v_pk_mul_f32 v[186:187], v[126:127], v[148:149] op_sel_hi:[1,0]
	v_pk_mul_f32 v[188:189], v[124:125], v[148:149] op_sel_hi:[1,0]
	v_pk_mul_f32 v[190:191], v[122:123], v[148:149] op_sel_hi:[1,0]
	v_pk_mul_f32 v[192:193], v[120:121], v[148:149] op_sel_hi:[1,0]
	v_pk_mul_f32 v[194:195], v[118:119], v[148:149] op_sel_hi:[1,0]
	v_pk_mul_f32 v[196:197], v[116:117], v[148:149] op_sel_hi:[1,0]
	s_cbranch_scc1 .LBB0_201
	v_pk_mul_f32 v[148:149], v[182:183], v[182:183]
	v_pk_mul_f32 v[150:151], v[184:185], v[184:185]
	v_mov_b32_e32 v153, v149
	v_mov_b32_e32 v152, v150
	v_pk_mov_b32 v[148:149], v[150:151], v[148:149] op_sel:[1,0]
	v_pk_mul_f32 v[150:151], v[186:187], v[186:187]
	v_pk_add_f32 v[148:149], v[148:149], v[152:153]
	v_pk_mul_f32 v[152:153], v[188:189], v[188:189]
	v_pk_add_f32 v[148:149], v[148:149], v[148:149] op_sel_hi:[0,1]
	v_mov_b32_e32 v154, v152
	v_mov_b32_e32 v155, v151
	v_pk_mov_b32 v[150:151], v[152:153], v[150:151] op_sel:[1,0]
	v_mul_f32_e32 v148, v192, v192
	v_pk_add_f32 v[150:151], v[150:151], v[154:155]
	v_pk_fma_f32 v[152:153], v[192:193], v[192:193], v[148:149] op_sel_hi:[1,1,0]
	v_mul_f32_e32 v148, v190, v190
	v_pk_add_f32 v[150:151], v[150:151], v[150:151] op_sel_hi:[0,1]
	v_pk_fma_f32 v[154:155], v[190:191], v[190:191], v[148:149] op_sel_hi:[1,1,0]
	v_mul_f32_e32 v152, v196, v196
	v_mul_f32_e32 v154, v197, v197
	v_mul_f32_e32 v148, v194, v194
	v_mul_f32_e32 v150, v195, v195
	v_pk_add_f32 v[152:153], v[152:153], v[154:155]
	v_pk_add_f32 v[148:149], v[148:149], v[150:151]
	v_and_b32_e32 v150, 64, v204
	v_pk_add_f32 v[148:149], v[152:153], v[148:149]
	v_add_u32_e32 v150, 64, v150
	v_add_f32_e32 v148, v148, v149
	v_xor_b32_e32 v149, 16, v204
	v_cmp_lt_i32_e32 vcc, v149, v150
	s_lshl_b32 s26, s24, 6
	v_lshl_add_u64 v[152:153], v[162:163], 0, s[26:27]
	v_cndmask_b32_e32 v149, v204, v149, vcc
	v_lshlrev_b32_e32 v149, 2, v149
	ds_bpermute_b32 v149, v149, v148
	global_load_dwordx4 v[152:155], v[152:153], off
	s_mov_b32 s40, s64
	s_mov_b32 s41, s64
	s_waitcnt lgkmcnt(0)
	v_add_f32_e32 v148, v148, v149
	v_xor_b32_e32 v149, 32, v204
	v_cmp_lt_i32_e32 vcc, v149, v150
	s_nop 1
	v_cndmask_b32_e32 v149, v204, v149, vcc
	v_lshlrev_b32_e32 v149, 2, v149
	ds_bpermute_b32 v149, v149, v148
	s_waitcnt lgkmcnt(0)
	v_add_f32_e32 v148, v148, v149
	v_fmamk_f32 v148, v148, 0x3c800000, v202
	v_rsq_f32_e32 v180, v148
	v_lshl_add_u64 v[148:149], v[160:161], 0, s[26:27]
	global_load_dwordx4 v[148:151], v[148:149], off
	global_load_dwordx4 v[218:221], v[164:165], off
	global_load_dwordx4 v[222:225], v[166:167], off
	v_pk_mul_f32 v[184:185], v[184:185], v[180:181] op_sel_hi:[1,0]
	v_pk_mul_f32 v[182:183], v[182:183], v[180:181] op_sel_hi:[1,0]
	v_pk_mul_f32 v[206:207], v[144:145], v[184:185]
	v_pk_mul_f32 v[198:199], v[146:147], v[182:183]
	v_pk_mul_f32 v[182:183], v[186:187], v[180:181] op_sel_hi:[1,0]
	v_pk_mul_f32 v[184:185], v[188:189], v[180:181] op_sel_hi:[1,0]
	v_pk_mul_f32 v[188:189], v[142:143], v[182:183]
	v_pk_mul_f32 v[186:187], v[140:141], v[184:185]
	v_pk_mul_f32 v[190:191], v[190:191], v[180:181] op_sel_hi:[1,0]
	v_pk_mul_f32 v[192:193], v[192:193], v[180:181] op_sel_hi:[1,0]
	s_waitcnt vmcnt(3)
	v_pk_mul_f32 v[182:183], v[154:155], v[188:189]
	v_pk_mul_f32 v[184:185], v[152:153], v[186:187]
	s_waitcnt vmcnt(2)
	v_pk_fma_f32 v[182:183], v[150:151], v[198:199], v[182:183] neg_lo:[0,0,1] neg_hi:[0,0,1]
	v_pk_fma_f32 v[184:185], v[148:149], v[206:207], v[184:185] neg_lo:[0,0,1] neg_hi:[0,0,1]
	v_pk_mul_f32 v[150:151], v[150:151], v[188:189]
	v_pk_mul_f32 v[148:149], v[148:149], v[186:187]
	v_pk_fma_f32 v[150:151], v[154:155], v[198:199], v[150:151]
	v_pk_fma_f32 v[148:149], v[152:153], v[206:207], v[148:149]
	v_pk_mul_f32 v[186:187], s[40:41], v[150:151]
	v_pk_mul_f32 v[188:189], s[64:65], v[148:149]
	s_nop 0
	v_pk_mul_f32 v[198:199], v[138:139], v[190:191]
	v_pk_mul_f32 v[190:191], v[194:195], v[180:181] op_sel_hi:[1,0]
	v_pk_mul_f32 v[180:181], v[196:197], v[180:181] op_sel_hi:[1,0]
	v_pk_mul_f32 v[194:195], v[134:135], v[190:191]
	v_pk_mul_f32 v[180:181], v[132:133], v[180:181]
	v_pk_mul_f32 v[206:207], v[136:137], v[192:193]
	v_pk_mul_f32 v[182:183], s[40:41], v[182:183]
	v_pk_mul_f32 v[184:185], s[64:65], v[184:185]
	s_waitcnt vmcnt(0)
	v_pk_mul_f32 v[190:191], v[224:225], v[194:195]
	v_pk_mul_f32 v[192:193], v[222:223], v[180:181]
	v_pk_fma_f32 v[190:191], v[220:221], v[198:199], v[190:191] neg_lo:[0,0,1] neg_hi:[0,0,1]
	v_pk_fma_f32 v[192:193], v[218:219], v[206:207], v[192:193] neg_lo:[0,0,1] neg_hi:[0,0,1]
	v_pk_mul_f32 v[150:151], v[220:221], v[194:195]
	v_pk_mul_f32 v[148:149], v[218:219], v[180:181]
	v_pk_fma_f32 v[150:151], v[224:225], v[198:199], v[150:151]
	v_pk_fma_f32 v[148:149], v[222:223], v[206:207], v[148:149]
	v_pk_mul_f32 v[190:191], s[40:41], v[190:191]
	v_pk_mul_f32 v[192:193], s[64:65], v[192:193]
	v_pk_mul_f32 v[194:195], s[40:41], v[150:151]
	v_pk_mul_f32 v[196:197], s[64:65], v[148:149]
.LBB0_201:
	v_lshlrev_b32_e32 v148, 1, v158
	v_mov_b32_e32 v149, v2
	v_lshl_add_u64 v[180:181], s[28:29], 0, v[148:149]
	v_mad_i64_i32 v[148:149], s[28:29], s62, v172, 0
	v_lshl_add_u64 v[148:149], v[148:149], 1, v[180:181]
	v_cvt_pk_bf16_f32 v150, v184, v185
	v_cvt_pk_bf16_f32 v151, v182, v183
	global_store_dwordx2 v[148:149], v[150:151], off
	v_cvt_pk_bf16_f32 v150, v188, v189
	v_cvt_pk_bf16_f32 v151, v186, v187
	global_store_dwordx2 v[148:149], v[150:151], off offset:32
	v_cvt_pk_bf16_f32 v150, v192, v193
	v_cvt_pk_bf16_f32 v151, v190, v191
	global_store_dwordx2 v[148:149], v[150:151], off offset:64
	v_cvt_pk_bf16_f32 v150, v196, v197
	v_cvt_pk_bf16_f32 v151, v194, v195
	global_store_dwordx2 v[148:149], v[150:151], off offset:96
	s_nop 0
	v_cndmask_b32_e64 v149, 0, 1, s[66:67]
	v_cmp_ne_u32_e64 s[40:41], 1, v149
	s_andn2_b64 vcc, exec, s[66:67]
	s_nop 1
	v_fmamk_f32 v148, v211, 0x3a800000, v202
	v_rsq_f32_e32 v148, v148
	s_nop 0
	v_pk_mul_f32 v[184:185], v[114:115], v[148:149] op_sel_hi:[1,0]
	v_pk_mul_f32 v[188:189], v[112:113], v[148:149] op_sel_hi:[1,0]
	v_pk_mul_f32 v[182:183], v[110:111], v[148:149] op_sel_hi:[1,0]
	v_pk_mul_f32 v[186:187], v[108:109], v[148:149] op_sel_hi:[1,0]
	v_pk_mul_f32 v[190:191], v[106:107], v[148:149] op_sel_hi:[1,0]
	v_pk_mul_f32 v[192:193], v[104:105], v[148:149] op_sel_hi:[1,0]
	v_pk_mul_f32 v[194:195], v[102:103], v[148:149] op_sel_hi:[1,0]
	v_pk_mul_f32 v[196:197], v[100:101], v[148:149] op_sel_hi:[1,0]
	s_cbranch_vccnz .LBB0_203
	v_pk_mul_f32 v[148:149], v[184:185], v[184:185]
	v_pk_mul_f32 v[150:151], v[188:189], v[188:189]
	v_mov_b32_e32 v153, v149
	v_mov_b32_e32 v152, v150
	v_pk_mov_b32 v[148:149], v[150:151], v[148:149] op_sel:[1,0]
	v_pk_mul_f32 v[150:151], v[182:183], v[182:183]
	v_pk_add_f32 v[148:149], v[148:149], v[152:153]
	v_pk_mul_f32 v[152:153], v[186:187], v[186:187]
	v_pk_add_f32 v[148:149], v[148:149], v[148:149] op_sel_hi:[0,1]
	v_mov_b32_e32 v154, v152
	v_mov_b32_e32 v155, v151
	v_pk_mov_b32 v[150:151], v[152:153], v[150:151] op_sel:[1,0]
	v_mul_f32_e32 v148, v192, v192
	v_pk_add_f32 v[150:151], v[150:151], v[154:155]
	v_pk_fma_f32 v[152:153], v[192:193], v[192:193], v[148:149] op_sel_hi:[1,1,0]
	v_mul_f32_e32 v148, v190, v190
	v_pk_add_f32 v[150:151], v[150:151], v[150:151] op_sel_hi:[0,1]
	v_pk_fma_f32 v[154:155], v[190:191], v[190:191], v[148:149] op_sel_hi:[1,1,0]
	v_mul_f32_e32 v152, v196, v196
	v_mul_f32_e32 v154, v197, v197
	v_mul_f32_e32 v148, v194, v194
	v_mul_f32_e32 v150, v195, v195
	v_pk_add_f32 v[152:153], v[152:153], v[154:155]
	v_pk_add_f32 v[148:149], v[148:149], v[150:151]
	v_and_b32_e32 v150, 64, v204
	v_pk_add_f32 v[148:149], v[152:153], v[148:149]
	v_add_u32_e32 v150, 64, v150
	v_add_f32_e32 v148, v148, v149
	v_xor_b32_e32 v149, 16, v204
	v_cmp_lt_i32_e32 vcc, v149, v150
	s_lshl_b32 s26, s24, 6
	v_lshl_add_u64 v[152:153], v[162:163], 0, s[26:27]
	v_cndmask_b32_e32 v149, v204, v149, vcc
	v_lshlrev_b32_e32 v149, 2, v149
	ds_bpermute_b32 v149, v149, v148
	global_load_dwordx4 v[152:155], v[152:153], off
	s_mov_b32 s28, s64
	s_mov_b32 s29, s64
	s_waitcnt lgkmcnt(0)
	v_add_f32_e32 v148, v148, v149
	v_xor_b32_e32 v149, 32, v204
	v_cmp_lt_i32_e32 vcc, v149, v150
	s_nop 1
	v_cndmask_b32_e32 v149, v204, v149, vcc
	v_lshlrev_b32_e32 v149, 2, v149
	ds_bpermute_b32 v149, v149, v148
	s_waitcnt lgkmcnt(0)
	v_add_f32_e32 v148, v148, v149
	v_fmamk_f32 v148, v148, 0x3c800000, v202
	v_rsq_f32_e32 v198, v148
	v_lshl_add_u64 v[148:149], v[160:161], 0, s[26:27]
	global_load_dwordx4 v[148:151], v[148:149], off
	global_load_dwordx4 v[218:221], v[164:165], off offset:1024
	global_load_dwordx4 v[222:225], v[166:167], off offset:1024
	v_pk_mul_f32 v[184:185], v[184:185], v[198:199] op_sel_hi:[1,0]
	s_nop 0
	v_pk_mul_f32 v[206:207], v[146:147], v[184:185]
	v_pk_mul_f32 v[182:183], v[182:183], v[198:199] op_sel_hi:[1,0]
	v_pk_mul_f32 v[184:185], v[186:187], v[198:199] op_sel_hi:[1,0]
	v_pk_mul_f32 v[188:189], v[188:189], v[198:199] op_sel_hi:[1,0]
	v_pk_mul_f32 v[186:187], v[140:141], v[184:185]
	v_pk_mul_f32 v[182:183], v[142:143], v[182:183]
	v_pk_mul_f32 v[208:209], v[144:145], v[188:189]
	v_pk_mul_f32 v[192:193], v[192:193], v[198:199] op_sel_hi:[1,0]
	v_pk_mul_f32 v[190:191], v[190:191], v[198:199] op_sel_hi:[1,0]
	s_waitcnt vmcnt(3)
	v_pk_mul_f32 v[184:185], v[154:155], v[182:183]
	v_pk_mul_f32 v[188:189], v[152:153], v[186:187]
	s_waitcnt vmcnt(2)
	v_pk_fma_f32 v[184:185], v[150:151], v[206:207], v[184:185] neg_lo:[0,0,1] neg_hi:[0,0,1]
	v_pk_fma_f32 v[188:189], v[148:149], v[208:209], v[188:189] neg_lo:[0,0,1] neg_hi:[0,0,1]
	v_pk_mul_f32 v[150:151], v[150:151], v[182:183]
	v_pk_mul_f32 v[148:149], v[148:149], v[186:187]
	v_pk_fma_f32 v[150:151], v[154:155], v[206:207], v[150:151]
	v_pk_fma_f32 v[148:149], v[152:153], v[208:209], v[148:149]
	v_pk_mul_f32 v[182:183], s[28:29], v[150:151]
	v_pk_mul_f32 v[186:187], s[64:65], v[148:149]
	s_nop 0
	v_pk_mul_f32 v[206:207], v[138:139], v[190:191]
	v_pk_mul_f32 v[208:209], v[136:137], v[192:193]
	v_pk_mul_f32 v[190:191], v[194:195], v[198:199] op_sel_hi:[1,0]
	v_pk_mul_f32 v[192:193], v[196:197], v[198:199] op_sel_hi:[1,0]
	v_pk_mul_f32 v[196:197], v[134:135], v[190:191]
	v_pk_mul_f32 v[194:195], v[132:133], v[192:193]
	v_pk_mul_f32 v[184:185], s[28:29], v[184:185]
	v_pk_mul_f32 v[188:189], s[64:65], v[188:189]
	s_waitcnt vmcnt(0)
	v_pk_mul_f32 v[190:191], v[224:225], v[196:197]
	v_pk_mul_f32 v[192:193], v[222:223], v[194:195]
	v_pk_fma_f32 v[190:191], v[220:221], v[206:207], v[190:191] neg_lo:[0,0,1] neg_hi:[0,0,1]
	v_pk_fma_f32 v[192:193], v[218:219], v[208:209], v[192:193] neg_lo:[0,0,1] neg_hi:[0,0,1]
	v_pk_mul_f32 v[150:151], v[220:221], v[196:197]
	v_pk_mul_f32 v[148:149], v[218:219], v[194:195]
	v_pk_fma_f32 v[150:151], v[224:225], v[206:207], v[150:151]
	v_pk_fma_f32 v[148:149], v[222:223], v[208:209], v[148:149]
	v_pk_mul_f32 v[190:191], s[28:29], v[190:191]
	v_pk_mul_f32 v[192:193], s[64:65], v[192:193]
	v_pk_mul_f32 v[194:195], s[28:29], v[150:151]
	v_pk_mul_f32 v[196:197], s[64:65], v[148:149]
.LBB0_203:
	v_or_b32_e32 v148, 16, v172
	v_mad_i64_i32 v[148:149], s[28:29], s62, v148, 0
	v_lshl_add_u64 v[148:149], v[148:149], 1, v[180:181]
	v_cvt_pk_bf16_f32 v150, v188, v189
	v_cvt_pk_bf16_f32 v151, v184, v185
	global_store_dwordx2 v[148:149], v[150:151], off
	v_cvt_pk_bf16_f32 v150, v186, v187
	v_cvt_pk_bf16_f32 v151, v182, v183
	global_store_dwordx2 v[148:149], v[150:151], off offset:32
	v_cvt_pk_bf16_f32 v150, v192, v193
	v_cvt_pk_bf16_f32 v151, v190, v191
	global_store_dwordx2 v[148:149], v[150:151], off offset:64
	v_cvt_pk_bf16_f32 v150, v196, v197
	v_cvt_pk_bf16_f32 v151, v194, v195
	global_store_dwordx2 v[148:149], v[150:151], off offset:96
	s_nop 0
	s_and_b64 vcc, exec, s[40:41]
	s_nop 1
	v_fmamk_f32 v148, v212, 0x3a800000, v202
	v_rsq_f32_e32 v148, v148
	s_nop 0
	v_pk_mul_f32 v[184:185], v[98:99], v[148:149] op_sel_hi:[1,0]
	v_pk_mul_f32 v[188:189], v[96:97], v[148:149] op_sel_hi:[1,0]
	v_pk_mul_f32 v[182:183], v[94:95], v[148:149] op_sel_hi:[1,0]
	v_pk_mul_f32 v[186:187], v[92:93], v[148:149] op_sel_hi:[1,0]
	v_pk_mul_f32 v[190:191], v[90:91], v[148:149] op_sel_hi:[1,0]
	v_pk_mul_f32 v[192:193], v[88:89], v[148:149] op_sel_hi:[1,0]
	v_pk_mul_f32 v[194:195], v[86:87], v[148:149] op_sel_hi:[1,0]
	v_pk_mul_f32 v[196:197], v[84:85], v[148:149] op_sel_hi:[1,0]
	s_cbranch_vccnz .LBB0_205
	v_pk_mul_f32 v[148:149], v[184:185], v[184:185]
	v_pk_mul_f32 v[150:151], v[188:189], v[188:189]
	v_mov_b32_e32 v153, v149
	v_mov_b32_e32 v152, v150
	v_pk_mov_b32 v[148:149], v[150:151], v[148:149] op_sel:[1,0]
	v_pk_mul_f32 v[150:151], v[182:183], v[182:183]
	v_pk_add_f32 v[148:149], v[148:149], v[152:153]
	v_pk_mul_f32 v[152:153], v[186:187], v[186:187]
	v_pk_add_f32 v[148:149], v[148:149], v[148:149] op_sel_hi:[0,1]
	v_mov_b32_e32 v154, v152
	v_mov_b32_e32 v155, v151
	v_pk_mov_b32 v[150:151], v[152:153], v[150:151] op_sel:[1,0]
	v_mul_f32_e32 v148, v192, v192
	v_pk_add_f32 v[150:151], v[150:151], v[154:155]
	v_pk_fma_f32 v[152:153], v[192:193], v[192:193], v[148:149] op_sel_hi:[1,1,0]
	v_mul_f32_e32 v148, v190, v190
	v_pk_add_f32 v[150:151], v[150:151], v[150:151] op_sel_hi:[0,1]
	v_pk_fma_f32 v[154:155], v[190:191], v[190:191], v[148:149] op_sel_hi:[1,1,0]
	v_mul_f32_e32 v152, v196, v196
	v_mul_f32_e32 v154, v197, v197
	v_mul_f32_e32 v148, v194, v194
	v_mul_f32_e32 v150, v195, v195
	v_pk_add_f32 v[152:153], v[152:153], v[154:155]
	v_pk_add_f32 v[148:149], v[148:149], v[150:151]
	v_and_b32_e32 v150, 64, v204
	v_pk_add_f32 v[148:149], v[152:153], v[148:149]
	v_add_u32_e32 v150, 64, v150
	v_add_f32_e32 v148, v148, v149
	v_xor_b32_e32 v149, 16, v204
	v_cmp_lt_i32_e32 vcc, v149, v150
	s_lshl_b32 s26, s24, 6
	v_lshl_add_u64 v[152:153], v[162:163], 0, s[26:27]
	v_cndmask_b32_e32 v149, v204, v149, vcc
	v_lshlrev_b32_e32 v149, 2, v149
	ds_bpermute_b32 v149, v149, v148
	global_load_dwordx4 v[152:155], v[152:153], off
	s_mov_b32 s28, s64
	s_mov_b32 s29, s64
	s_waitcnt lgkmcnt(0)
	v_add_f32_e32 v148, v148, v149
	v_xor_b32_e32 v149, 32, v204
	v_cmp_lt_i32_e32 vcc, v149, v150
	s_nop 1
	v_cndmask_b32_e32 v149, v204, v149, vcc
	v_lshlrev_b32_e32 v149, 2, v149
	ds_bpermute_b32 v149, v149, v148
	s_waitcnt lgkmcnt(0)
	v_add_f32_e32 v148, v148, v149
	v_fmamk_f32 v148, v148, 0x3c800000, v202
	v_rsq_f32_e32 v198, v148
	v_lshl_add_u64 v[148:149], v[160:161], 0, s[26:27]
	global_load_dwordx4 v[148:151], v[148:149], off
	global_load_dwordx4 v[218:221], v[164:165], off offset:2048
	global_load_dwordx4 v[222:225], v[166:167], off offset:2048
	v_pk_mul_f32 v[184:185], v[184:185], v[198:199] op_sel_hi:[1,0]
	s_nop 0
	v_pk_mul_f32 v[206:207], v[146:147], v[184:185]
	v_pk_mul_f32 v[182:183], v[182:183], v[198:199] op_sel_hi:[1,0]
	v_pk_mul_f32 v[184:185], v[186:187], v[198:199] op_sel_hi:[1,0]
	v_pk_mul_f32 v[188:189], v[188:189], v[198:199] op_sel_hi:[1,0]
	v_pk_mul_f32 v[186:187], v[140:141], v[184:185]
	v_pk_mul_f32 v[182:183], v[142:143], v[182:183]
	v_pk_mul_f32 v[208:209], v[144:145], v[188:189]
	v_pk_mul_f32 v[192:193], v[192:193], v[198:199] op_sel_hi:[1,0]
	v_pk_mul_f32 v[190:191], v[190:191], v[198:199] op_sel_hi:[1,0]
	s_waitcnt vmcnt(3)
	v_pk_mul_f32 v[184:185], v[154:155], v[182:183]
	v_pk_mul_f32 v[188:189], v[152:153], v[186:187]
	s_waitcnt vmcnt(2)
	v_pk_fma_f32 v[184:185], v[150:151], v[206:207], v[184:185] neg_lo:[0,0,1] neg_hi:[0,0,1]
	v_pk_fma_f32 v[188:189], v[148:149], v[208:209], v[188:189] neg_lo:[0,0,1] neg_hi:[0,0,1]
	v_pk_mul_f32 v[150:151], v[150:151], v[182:183]
	v_pk_mul_f32 v[148:149], v[148:149], v[186:187]
	v_pk_fma_f32 v[150:151], v[154:155], v[206:207], v[150:151]
	v_pk_fma_f32 v[148:149], v[152:153], v[208:209], v[148:149]
	v_pk_mul_f32 v[182:183], s[28:29], v[150:151]
	v_pk_mul_f32 v[186:187], s[64:65], v[148:149]
	s_nop 0
	v_pk_mul_f32 v[206:207], v[138:139], v[190:191]
	v_pk_mul_f32 v[208:209], v[136:137], v[192:193]
	v_pk_mul_f32 v[190:191], v[194:195], v[198:199] op_sel_hi:[1,0]
	v_pk_mul_f32 v[192:193], v[196:197], v[198:199] op_sel_hi:[1,0]
	v_pk_mul_f32 v[196:197], v[134:135], v[190:191]
	v_pk_mul_f32 v[194:195], v[132:133], v[192:193]
	v_pk_mul_f32 v[184:185], s[28:29], v[184:185]
	v_pk_mul_f32 v[188:189], s[64:65], v[188:189]
	s_waitcnt vmcnt(0)
	v_pk_mul_f32 v[190:191], v[224:225], v[196:197]
	v_pk_mul_f32 v[192:193], v[222:223], v[194:195]
	v_pk_fma_f32 v[190:191], v[220:221], v[206:207], v[190:191] neg_lo:[0,0,1] neg_hi:[0,0,1]
	v_pk_fma_f32 v[192:193], v[218:219], v[208:209], v[192:193] neg_lo:[0,0,1] neg_hi:[0,0,1]
	v_pk_mul_f32 v[150:151], v[220:221], v[196:197]
	v_pk_mul_f32 v[148:149], v[218:219], v[194:195]
	v_pk_fma_f32 v[150:151], v[224:225], v[206:207], v[150:151]
	v_pk_fma_f32 v[148:149], v[222:223], v[208:209], v[148:149]
	v_pk_mul_f32 v[190:191], s[28:29], v[190:191]
	v_pk_mul_f32 v[192:193], s[64:65], v[192:193]
	v_pk_mul_f32 v[194:195], s[28:29], v[150:151]
	v_pk_mul_f32 v[196:197], s[64:65], v[148:149]
.LBB0_205:
	v_or_b32_e32 v148, 32, v172
	v_mad_i64_i32 v[148:149], s[28:29], s62, v148, 0
	v_lshl_add_u64 v[148:149], v[148:149], 1, v[180:181]
	v_cvt_pk_bf16_f32 v150, v188, v189
	v_cvt_pk_bf16_f32 v151, v184, v185
	global_store_dwordx2 v[148:149], v[150:151], off
	v_cvt_pk_bf16_f32 v150, v186, v187
	v_cvt_pk_bf16_f32 v151, v182, v183
	global_store_dwordx2 v[148:149], v[150:151], off offset:32
	v_cvt_pk_bf16_f32 v150, v192, v193
	v_cvt_pk_bf16_f32 v151, v190, v191
	global_store_dwordx2 v[148:149], v[150:151], off offset:64
	v_cvt_pk_bf16_f32 v150, v196, v197
	v_cvt_pk_bf16_f32 v151, v194, v195
	global_store_dwordx2 v[148:149], v[150:151], off offset:96
	s_nop 0
	s_and_b64 vcc, exec, s[40:41]
	s_nop 1
	v_fmamk_f32 v148, v213, 0x3a800000, v202
	v_rsq_f32_e32 v148, v148
	s_nop 0
	v_pk_mul_f32 v[184:185], v[82:83], v[148:149] op_sel_hi:[1,0]
	v_pk_mul_f32 v[188:189], v[80:81], v[148:149] op_sel_hi:[1,0]
	v_pk_mul_f32 v[182:183], v[78:79], v[148:149] op_sel_hi:[1,0]
	v_pk_mul_f32 v[186:187], v[76:77], v[148:149] op_sel_hi:[1,0]
	v_pk_mul_f32 v[190:191], v[74:75], v[148:149] op_sel_hi:[1,0]
	v_pk_mul_f32 v[192:193], v[72:73], v[148:149] op_sel_hi:[1,0]
	v_pk_mul_f32 v[194:195], v[70:71], v[148:149] op_sel_hi:[1,0]
	v_pk_mul_f32 v[196:197], v[68:69], v[148:149] op_sel_hi:[1,0]
	s_cbranch_vccnz .LBB0_207
	v_pk_mul_f32 v[148:149], v[184:185], v[184:185]
	v_pk_mul_f32 v[150:151], v[188:189], v[188:189]
	v_mov_b32_e32 v153, v149
	v_mov_b32_e32 v152, v150
	v_pk_mov_b32 v[148:149], v[150:151], v[148:149] op_sel:[1,0]
	v_pk_mul_f32 v[150:151], v[182:183], v[182:183]
	v_pk_add_f32 v[148:149], v[148:149], v[152:153]
	v_pk_mul_f32 v[152:153], v[186:187], v[186:187]
	v_pk_add_f32 v[148:149], v[148:149], v[148:149] op_sel_hi:[0,1]
	v_mov_b32_e32 v154, v152
	v_mov_b32_e32 v155, v151
	v_pk_mov_b32 v[150:151], v[152:153], v[150:151] op_sel:[1,0]
	v_mul_f32_e32 v148, v192, v192
	v_pk_add_f32 v[150:151], v[150:151], v[154:155]
	v_pk_fma_f32 v[152:153], v[192:193], v[192:193], v[148:149] op_sel_hi:[1,1,0]
	v_mul_f32_e32 v148, v190, v190
	v_pk_add_f32 v[150:151], v[150:151], v[150:151] op_sel_hi:[0,1]
	v_pk_fma_f32 v[154:155], v[190:191], v[190:191], v[148:149] op_sel_hi:[1,1,0]
	v_mul_f32_e32 v152, v196, v196
	v_mul_f32_e32 v154, v197, v197
	v_mul_f32_e32 v148, v194, v194
	v_mul_f32_e32 v150, v195, v195
	v_pk_add_f32 v[152:153], v[152:153], v[154:155]
	v_pk_add_f32 v[148:149], v[148:149], v[150:151]
	v_and_b32_e32 v150, 64, v204
	v_pk_add_f32 v[148:149], v[152:153], v[148:149]
	v_add_u32_e32 v150, 64, v150
	v_add_f32_e32 v148, v148, v149
	v_xor_b32_e32 v149, 16, v204
	v_cmp_lt_i32_e32 vcc, v149, v150
	s_lshl_b32 s26, s24, 6
	v_lshl_add_u64 v[152:153], v[162:163], 0, s[26:27]
	v_cndmask_b32_e32 v149, v204, v149, vcc
	v_lshlrev_b32_e32 v149, 2, v149
	ds_bpermute_b32 v149, v149, v148
	global_load_dwordx4 v[152:155], v[152:153], off
	s_mov_b32 s28, s64
	s_mov_b32 s29, s64
	s_waitcnt lgkmcnt(0)
	v_add_f32_e32 v148, v148, v149
	v_xor_b32_e32 v149, 32, v204
	v_cmp_lt_i32_e32 vcc, v149, v150
	s_nop 1
	v_cndmask_b32_e32 v149, v204, v149, vcc
	v_lshlrev_b32_e32 v149, 2, v149
	ds_bpermute_b32 v149, v149, v148
	s_waitcnt lgkmcnt(0)
	v_add_f32_e32 v148, v148, v149
	v_fmamk_f32 v148, v148, 0x3c800000, v202
	v_rsq_f32_e32 v198, v148
	v_lshl_add_u64 v[148:149], v[160:161], 0, s[26:27]
	global_load_dwordx4 v[148:151], v[148:149], off
	global_load_dwordx4 v[218:221], v[164:165], off offset:3072
	global_load_dwordx4 v[222:225], v[166:167], off offset:3072
	v_pk_mul_f32 v[184:185], v[184:185], v[198:199] op_sel_hi:[1,0]
	s_nop 0
	v_pk_mul_f32 v[206:207], v[146:147], v[184:185]
	v_pk_mul_f32 v[182:183], v[182:183], v[198:199] op_sel_hi:[1,0]
	v_pk_mul_f32 v[184:185], v[186:187], v[198:199] op_sel_hi:[1,0]
	v_pk_mul_f32 v[188:189], v[188:189], v[198:199] op_sel_hi:[1,0]
	v_pk_mul_f32 v[186:187], v[140:141], v[184:185]
	v_pk_mul_f32 v[182:183], v[142:143], v[182:183]
	v_pk_mul_f32 v[208:209], v[144:145], v[188:189]
	v_pk_mul_f32 v[192:193], v[192:193], v[198:199] op_sel_hi:[1,0]
	v_pk_mul_f32 v[190:191], v[190:191], v[198:199] op_sel_hi:[1,0]
	s_waitcnt vmcnt(3)
	v_pk_mul_f32 v[184:185], v[154:155], v[182:183]
	v_pk_mul_f32 v[188:189], v[152:153], v[186:187]
	s_waitcnt vmcnt(2)
	v_pk_fma_f32 v[184:185], v[150:151], v[206:207], v[184:185] neg_lo:[0,0,1] neg_hi:[0,0,1]
	v_pk_fma_f32 v[188:189], v[148:149], v[208:209], v[188:189] neg_lo:[0,0,1] neg_hi:[0,0,1]
	v_pk_mul_f32 v[150:151], v[150:151], v[182:183]
	v_pk_mul_f32 v[148:149], v[148:149], v[186:187]
	v_pk_fma_f32 v[150:151], v[154:155], v[206:207], v[150:151]
	v_pk_fma_f32 v[148:149], v[152:153], v[208:209], v[148:149]
	v_pk_mul_f32 v[182:183], s[28:29], v[150:151]
	v_pk_mul_f32 v[186:187], s[64:65], v[148:149]
	s_nop 0
	v_pk_mul_f32 v[206:207], v[138:139], v[190:191]
	v_pk_mul_f32 v[208:209], v[136:137], v[192:193]
	v_pk_mul_f32 v[190:191], v[194:195], v[198:199] op_sel_hi:[1,0]
	v_pk_mul_f32 v[192:193], v[196:197], v[198:199] op_sel_hi:[1,0]
	v_pk_mul_f32 v[196:197], v[134:135], v[190:191]
	v_pk_mul_f32 v[194:195], v[132:133], v[192:193]
	v_pk_mul_f32 v[184:185], s[28:29], v[184:185]
	v_pk_mul_f32 v[188:189], s[64:65], v[188:189]
	s_waitcnt vmcnt(0)
	v_pk_mul_f32 v[190:191], v[224:225], v[196:197]
	v_pk_mul_f32 v[192:193], v[222:223], v[194:195]
	v_pk_fma_f32 v[190:191], v[220:221], v[206:207], v[190:191] neg_lo:[0,0,1] neg_hi:[0,0,1]
	v_pk_fma_f32 v[192:193], v[218:219], v[208:209], v[192:193] neg_lo:[0,0,1] neg_hi:[0,0,1]
	v_pk_mul_f32 v[150:151], v[220:221], v[196:197]
	v_pk_mul_f32 v[148:149], v[218:219], v[194:195]
	v_pk_fma_f32 v[150:151], v[224:225], v[206:207], v[150:151]
	v_pk_fma_f32 v[148:149], v[222:223], v[208:209], v[148:149]
	v_pk_mul_f32 v[190:191], s[28:29], v[190:191]
	v_pk_mul_f32 v[192:193], s[64:65], v[192:193]
	v_pk_mul_f32 v[194:195], s[28:29], v[150:151]
	v_pk_mul_f32 v[196:197], s[64:65], v[148:149]
.LBB0_207:
	v_or_b32_e32 v148, 48, v172
	v_mad_i64_i32 v[148:149], s[24:25], s62, v148, 0
	v_lshl_add_u64 v[148:149], v[148:149], 1, v[180:181]
	v_cvt_pk_bf16_f32 v150, v188, v189
	v_cvt_pk_bf16_f32 v151, v184, v185
	global_store_dwordx2 v[148:149], v[150:151], off
	v_cvt_pk_bf16_f32 v150, v186, v187
	v_cvt_pk_bf16_f32 v151, v182, v183
	global_store_dwordx2 v[148:149], v[150:151], off offset:32
	v_cvt_pk_bf16_f32 v150, v192, v193
	v_cvt_pk_bf16_f32 v151, v190, v191
	global_store_dwordx2 v[148:149], v[150:151], off offset:64
	v_cvt_pk_bf16_f32 v150, v196, v197
	v_cvt_pk_bf16_f32 v151, v194, v195
	global_store_dwordx2 v[148:149], v[150:151], off offset:96
	s_nop 0
	v_add_u32_e32 v173, 0x80, v172
	v_bfe_u32 v149, v173, 6, 8
	s_and_b64 vcc, exec, s[40:41]
	v_lshlrev_b32_e32 v182, 6, v149
	s_nop 1
	v_fmamk_f32 v148, v214, 0x3a800000, v202
	v_rsq_f32_e32 v148, v148
	s_nop 0
	v_pk_mul_f32 v[186:187], v[66:67], v[148:149] op_sel_hi:[1,0]
	v_pk_mul_f32 v[190:191], v[64:65], v[148:149] op_sel_hi:[1,0]
	v_pk_mul_f32 v[184:185], v[62:63], v[148:149] op_sel_hi:[1,0]
	v_pk_mul_f32 v[188:189], v[60:61], v[148:149] op_sel_hi:[1,0]
	v_pk_mul_f32 v[192:193], v[58:59], v[148:149] op_sel_hi:[1,0]
	v_pk_mul_f32 v[194:195], v[56:57], v[148:149] op_sel_hi:[1,0]
	v_pk_mul_f32 v[196:197], v[54:55], v[148:149] op_sel_hi:[1,0]
	v_pk_mul_f32 v[198:199], v[52:53], v[148:149] op_sel_hi:[1,0]
	s_cbranch_vccnz .LBB0_209
	v_pk_mul_f32 v[148:149], v[186:187], v[186:187]
	v_pk_mul_f32 v[150:151], v[190:191], v[190:191]
	v_mov_b32_e32 v153, v149
	v_mov_b32_e32 v152, v150
	v_pk_mov_b32 v[148:149], v[150:151], v[148:149] op_sel:[1,0]
	v_pk_mul_f32 v[150:151], v[184:185], v[184:185]
	v_pk_add_f32 v[148:149], v[148:149], v[152:153]
	v_pk_mul_f32 v[152:153], v[188:189], v[188:189]
	v_pk_add_f32 v[148:149], v[148:149], v[148:149] op_sel_hi:[0,1]
	v_mov_b32_e32 v154, v152
	v_mov_b32_e32 v155, v151
	v_pk_mov_b32 v[150:151], v[152:153], v[150:151] op_sel:[1,0]
	v_mul_f32_e32 v148, v194, v194
	v_pk_add_f32 v[150:151], v[150:151], v[154:155]
	v_pk_fma_f32 v[152:153], v[194:195], v[194:195], v[148:149] op_sel_hi:[1,1,0]
	v_mul_f32_e32 v148, v192, v192
	v_pk_add_f32 v[150:151], v[150:151], v[150:151] op_sel_hi:[0,1]
	v_pk_fma_f32 v[154:155], v[192:193], v[192:193], v[148:149] op_sel_hi:[1,1,0]
	v_mul_f32_e32 v152, v198, v198
	v_mul_f32_e32 v154, v199, v199
	v_mul_f32_e32 v148, v196, v196
	v_mul_f32_e32 v150, v197, v197
	v_pk_add_f32 v[152:153], v[152:153], v[154:155]
	v_pk_add_f32 v[148:149], v[148:149], v[150:151]
	v_and_b32_e32 v150, 64, v204
	v_pk_add_f32 v[148:149], v[152:153], v[148:149]
	v_add_u32_e32 v150, 64, v150
	v_add_f32_e32 v148, v148, v149
	v_xor_b32_e32 v149, 16, v204
	v_cmp_lt_i32_e32 vcc, v149, v150
	v_mov_b32_e32 v183, v2
	v_lshl_add_u64 v[152:153], v[162:163], 0, v[182:183]
	v_cndmask_b32_e32 v149, v204, v149, vcc
	v_lshlrev_b32_e32 v149, 2, v149
	ds_bpermute_b32 v149, v149, v148
	global_load_dwordx4 v[152:155], v[152:153], off
	s_mov_b32 s28, s64
	s_mov_b32 s29, s64
	s_waitcnt lgkmcnt(0)
	v_add_f32_e32 v148, v148, v149
	v_xor_b32_e32 v149, 32, v204
	v_cmp_lt_i32_e32 vcc, v149, v150
	s_nop 1
	v_cndmask_b32_e32 v149, v204, v149, vcc
	v_lshlrev_b32_e32 v149, 2, v149
	ds_bpermute_b32 v149, v149, v148
	s_waitcnt lgkmcnt(0)
	v_add_f32_e32 v148, v148, v149
	v_fmamk_f32 v148, v148, 0x3c800000, v202
	v_rsq_f32_e32 v200, v148
	v_lshl_add_u64 v[148:149], v[160:161], 0, v[182:183]
	global_load_dwordx4 v[148:151], v[148:149], off
	global_load_dwordx4 v[218:221], v[164:165], off
	global_load_dwordx4 v[222:225], v[166:167], off
	v_pk_mul_f32 v[186:187], v[186:187], v[200:201] op_sel_hi:[1,0]
	s_nop 0
	v_pk_mul_f32 v[206:207], v[146:147], v[186:187]
	v_pk_mul_f32 v[184:185], v[184:185], v[200:201] op_sel_hi:[1,0]
	v_pk_mul_f32 v[186:187], v[188:189], v[200:201] op_sel_hi:[1,0]
	v_pk_mul_f32 v[190:191], v[190:191], v[200:201] op_sel_hi:[1,0]
	v_pk_mul_f32 v[188:189], v[140:141], v[186:187]
	v_pk_mul_f32 v[184:185], v[142:143], v[184:185]
	v_pk_mul_f32 v[208:209], v[144:145], v[190:191]
	v_pk_mul_f32 v[194:195], v[194:195], v[200:201] op_sel_hi:[1,0]
	v_pk_mul_f32 v[192:193], v[192:193], v[200:201] op_sel_hi:[1,0]
	s_waitcnt vmcnt(3)
	v_pk_mul_f32 v[186:187], v[154:155], v[184:185]
	v_pk_mul_f32 v[190:191], v[152:153], v[188:189]
	s_waitcnt vmcnt(2)
	v_pk_fma_f32 v[186:187], v[150:151], v[206:207], v[186:187] neg_lo:[0,0,1] neg_hi:[0,0,1]
	v_pk_fma_f32 v[190:191], v[148:149], v[208:209], v[190:191] neg_lo:[0,0,1] neg_hi:[0,0,1]
	v_pk_mul_f32 v[150:151], v[150:151], v[184:185]
	v_pk_mul_f32 v[148:149], v[148:149], v[188:189]
	v_pk_fma_f32 v[150:151], v[154:155], v[206:207], v[150:151]
	v_pk_fma_f32 v[148:149], v[152:153], v[208:209], v[148:149]
	v_pk_mul_f32 v[184:185], s[28:29], v[150:151]
	v_pk_mul_f32 v[188:189], s[64:65], v[148:149]
	s_nop 0
	v_pk_mul_f32 v[206:207], v[138:139], v[192:193]
	v_pk_mul_f32 v[208:209], v[136:137], v[194:195]
	v_pk_mul_f32 v[192:193], v[196:197], v[200:201] op_sel_hi:[1,0]
	v_pk_mul_f32 v[194:195], v[198:199], v[200:201] op_sel_hi:[1,0]
	v_pk_mul_f32 v[198:199], v[134:135], v[192:193]
	v_pk_mul_f32 v[196:197], v[132:133], v[194:195]
	v_pk_mul_f32 v[186:187], s[28:29], v[186:187]
	v_pk_mul_f32 v[190:191], s[64:65], v[190:191]
	s_waitcnt vmcnt(0)
	v_pk_mul_f32 v[192:193], v[224:225], v[198:199]
	v_pk_mul_f32 v[194:195], v[222:223], v[196:197]
	v_pk_fma_f32 v[192:193], v[220:221], v[206:207], v[192:193] neg_lo:[0,0,1] neg_hi:[0,0,1]
	v_pk_fma_f32 v[194:195], v[218:219], v[208:209], v[194:195] neg_lo:[0,0,1] neg_hi:[0,0,1]
	v_pk_mul_f32 v[150:151], v[220:221], v[198:199]
	v_pk_mul_f32 v[148:149], v[218:219], v[196:197]
	v_pk_fma_f32 v[150:151], v[224:225], v[206:207], v[150:151]
	v_pk_fma_f32 v[148:149], v[222:223], v[208:209], v[148:149]
	v_pk_mul_f32 v[192:193], s[28:29], v[192:193]
	v_pk_mul_f32 v[194:195], s[64:65], v[194:195]
	v_pk_mul_f32 v[196:197], s[28:29], v[150:151]
	v_pk_mul_f32 v[198:199], s[64:65], v[148:149]
.LBB0_209:
	v_mad_i64_i32 v[148:149], s[24:25], s62, v173, 0
	v_lshl_add_u64 v[148:149], v[148:149], 1, v[180:181]
	v_cvt_pk_bf16_f32 v150, v190, v191
	v_cvt_pk_bf16_f32 v151, v186, v187
	global_store_dwordx2 v[148:149], v[150:151], off
	v_cvt_pk_bf16_f32 v150, v188, v189
	v_cvt_pk_bf16_f32 v151, v184, v185
	global_store_dwordx2 v[148:149], v[150:151], off offset:32
	v_cvt_pk_bf16_f32 v150, v194, v195
	v_cvt_pk_bf16_f32 v151, v192, v193
	global_store_dwordx2 v[148:149], v[150:151], off offset:64
	v_cvt_pk_bf16_f32 v150, v198, v199
	v_cvt_pk_bf16_f32 v151, v196, v197
	global_store_dwordx2 v[148:149], v[150:151], off offset:96
	s_nop 0
	s_and_b64 vcc, exec, s[40:41]
	s_nop 1
	v_fmamk_f32 v148, v215, 0x3a800000, v202
	v_rsq_f32_e32 v148, v148
	s_nop 0
	v_pk_mul_f32 v[186:187], v[50:51], v[148:149] op_sel_hi:[1,0]
	v_pk_mul_f32 v[190:191], v[48:49], v[148:149] op_sel_hi:[1,0]
	v_pk_mul_f32 v[184:185], v[46:47], v[148:149] op_sel_hi:[1,0]
	v_pk_mul_f32 v[188:189], v[44:45], v[148:149] op_sel_hi:[1,0]
	v_pk_mul_f32 v[192:193], v[42:43], v[148:149] op_sel_hi:[1,0]
	v_pk_mul_f32 v[194:195], v[40:41], v[148:149] op_sel_hi:[1,0]
	v_pk_mul_f32 v[196:197], v[38:39], v[148:149] op_sel_hi:[1,0]
	v_pk_mul_f32 v[198:199], v[36:37], v[148:149] op_sel_hi:[1,0]
	s_cbranch_vccnz .LBB0_211
	v_pk_mul_f32 v[148:149], v[186:187], v[186:187]
	v_pk_mul_f32 v[150:151], v[190:191], v[190:191]
	v_mov_b32_e32 v153, v149
	v_mov_b32_e32 v152, v150
	v_pk_mov_b32 v[148:149], v[150:151], v[148:149] op_sel:[1,0]
	v_pk_mul_f32 v[150:151], v[184:185], v[184:185]
	v_pk_add_f32 v[148:149], v[148:149], v[152:153]
	v_pk_mul_f32 v[152:153], v[188:189], v[188:189]
	v_pk_add_f32 v[148:149], v[148:149], v[148:149] op_sel_hi:[0,1]
	v_mov_b32_e32 v154, v152
	v_mov_b32_e32 v155, v151
	v_pk_mov_b32 v[150:151], v[152:153], v[150:151] op_sel:[1,0]
	v_mul_f32_e32 v148, v194, v194
	v_pk_add_f32 v[150:151], v[150:151], v[154:155]
	v_pk_fma_f32 v[152:153], v[194:195], v[194:195], v[148:149] op_sel_hi:[1,1,0]
	v_mul_f32_e32 v148, v192, v192
	v_pk_add_f32 v[150:151], v[150:151], v[150:151] op_sel_hi:[0,1]
	v_pk_fma_f32 v[154:155], v[192:193], v[192:193], v[148:149] op_sel_hi:[1,1,0]
	v_mul_f32_e32 v152, v198, v198
	v_mul_f32_e32 v154, v199, v199
	v_mul_f32_e32 v148, v196, v196
	v_mul_f32_e32 v150, v197, v197
	v_pk_add_f32 v[152:153], v[152:153], v[154:155]
	v_pk_add_f32 v[148:149], v[148:149], v[150:151]
	v_and_b32_e32 v150, 64, v204
	v_pk_add_f32 v[148:149], v[152:153], v[148:149]
	v_add_u32_e32 v150, 64, v150
	v_add_f32_e32 v148, v148, v149
	v_xor_b32_e32 v149, 16, v204
	v_cmp_lt_i32_e32 vcc, v149, v150
	v_mov_b32_e32 v183, v2
	v_lshl_add_u64 v[152:153], v[162:163], 0, v[182:183]
	v_cndmask_b32_e32 v149, v204, v149, vcc
	v_lshlrev_b32_e32 v149, 2, v149
	ds_bpermute_b32 v149, v149, v148
	global_load_dwordx4 v[152:155], v[152:153], off
	s_mov_b32 s28, s64
	s_mov_b32 s29, s64
	s_waitcnt lgkmcnt(0)
	v_add_f32_e32 v148, v148, v149
	v_xor_b32_e32 v149, 32, v204
	v_cmp_lt_i32_e32 vcc, v149, v150
	s_nop 1
	v_cndmask_b32_e32 v149, v204, v149, vcc
	v_lshlrev_b32_e32 v149, 2, v149
	ds_bpermute_b32 v149, v149, v148
	s_waitcnt lgkmcnt(0)
	v_add_f32_e32 v148, v148, v149
	v_fmamk_f32 v148, v148, 0x3c800000, v202
	v_rsq_f32_e32 v200, v148
	v_lshl_add_u64 v[148:149], v[160:161], 0, v[182:183]
	global_load_dwordx4 v[148:151], v[148:149], off
	global_load_dwordx4 v[218:221], v[164:165], off offset:1024
	global_load_dwordx4 v[222:225], v[166:167], off offset:1024
	v_pk_mul_f32 v[186:187], v[186:187], v[200:201] op_sel_hi:[1,0]
	s_nop 0
	v_pk_mul_f32 v[206:207], v[146:147], v[186:187]
	v_pk_mul_f32 v[184:185], v[184:185], v[200:201] op_sel_hi:[1,0]
	v_pk_mul_f32 v[186:187], v[188:189], v[200:201] op_sel_hi:[1,0]
	v_pk_mul_f32 v[190:191], v[190:191], v[200:201] op_sel_hi:[1,0]
	v_pk_mul_f32 v[188:189], v[140:141], v[186:187]
	v_pk_mul_f32 v[184:185], v[142:143], v[184:185]
	v_pk_mul_f32 v[208:209], v[144:145], v[190:191]
	v_pk_mul_f32 v[194:195], v[194:195], v[200:201] op_sel_hi:[1,0]
	v_pk_mul_f32 v[192:193], v[192:193], v[200:201] op_sel_hi:[1,0]
	s_waitcnt vmcnt(3)
	v_pk_mul_f32 v[186:187], v[154:155], v[184:185]
	v_pk_mul_f32 v[190:191], v[152:153], v[188:189]
	s_waitcnt vmcnt(2)
	v_pk_fma_f32 v[186:187], v[150:151], v[206:207], v[186:187] neg_lo:[0,0,1] neg_hi:[0,0,1]
	v_pk_fma_f32 v[190:191], v[148:149], v[208:209], v[190:191] neg_lo:[0,0,1] neg_hi:[0,0,1]
	v_pk_mul_f32 v[150:151], v[150:151], v[184:185]
	v_pk_mul_f32 v[148:149], v[148:149], v[188:189]
	v_pk_fma_f32 v[150:151], v[154:155], v[206:207], v[150:151]
	v_pk_fma_f32 v[148:149], v[152:153], v[208:209], v[148:149]
	v_pk_mul_f32 v[184:185], s[28:29], v[150:151]
	v_pk_mul_f32 v[188:189], s[64:65], v[148:149]
	s_nop 0
	v_pk_mul_f32 v[206:207], v[138:139], v[192:193]
	v_pk_mul_f32 v[208:209], v[136:137], v[194:195]
	v_pk_mul_f32 v[192:193], v[196:197], v[200:201] op_sel_hi:[1,0]
	v_pk_mul_f32 v[194:195], v[198:199], v[200:201] op_sel_hi:[1,0]
	v_pk_mul_f32 v[198:199], v[134:135], v[192:193]
	v_pk_mul_f32 v[196:197], v[132:133], v[194:195]
	v_pk_mul_f32 v[186:187], s[28:29], v[186:187]
	v_pk_mul_f32 v[190:191], s[64:65], v[190:191]
	s_waitcnt vmcnt(0)
	v_pk_mul_f32 v[192:193], v[224:225], v[198:199]
	v_pk_mul_f32 v[194:195], v[222:223], v[196:197]
	v_pk_fma_f32 v[192:193], v[220:221], v[206:207], v[192:193] neg_lo:[0,0,1] neg_hi:[0,0,1]
	v_pk_fma_f32 v[194:195], v[218:219], v[208:209], v[194:195] neg_lo:[0,0,1] neg_hi:[0,0,1]
	v_pk_mul_f32 v[150:151], v[220:221], v[198:199]
	v_pk_mul_f32 v[148:149], v[218:219], v[196:197]
	v_pk_fma_f32 v[150:151], v[224:225], v[206:207], v[150:151]
	v_pk_fma_f32 v[148:149], v[222:223], v[208:209], v[148:149]
	v_pk_mul_f32 v[192:193], s[28:29], v[192:193]
	v_pk_mul_f32 v[194:195], s[64:65], v[194:195]
	v_pk_mul_f32 v[196:197], s[28:29], v[150:151]
	v_pk_mul_f32 v[198:199], s[64:65], v[148:149]
.LBB0_211:
	v_add_u32_e32 v148, 0x90, v172
	v_mad_i64_i32 v[148:149], s[24:25], s62, v148, 0
	v_lshl_add_u64 v[148:149], v[148:149], 1, v[180:181]
	v_cvt_pk_bf16_f32 v150, v190, v191
	v_cvt_pk_bf16_f32 v151, v186, v187
	global_store_dwordx2 v[148:149], v[150:151], off
	v_cvt_pk_bf16_f32 v150, v188, v189
	v_cvt_pk_bf16_f32 v151, v184, v185
	global_store_dwordx2 v[148:149], v[150:151], off offset:32
	v_cvt_pk_bf16_f32 v150, v194, v195
	v_cvt_pk_bf16_f32 v151, v192, v193
	global_store_dwordx2 v[148:149], v[150:151], off offset:64
	v_cvt_pk_bf16_f32 v150, v198, v199
	v_cvt_pk_bf16_f32 v151, v196, v197
	global_store_dwordx2 v[148:149], v[150:151], off offset:96
	s_nop 0
	s_and_b64 vcc, exec, s[40:41]
	s_nop 1
	v_fmamk_f32 v148, v216, 0x3a800000, v202
	v_rsq_f32_e32 v148, v148
	s_nop 0
	v_pk_mul_f32 v[186:187], v[34:35], v[148:149] op_sel_hi:[1,0]
	v_pk_mul_f32 v[190:191], v[32:33], v[148:149] op_sel_hi:[1,0]
	v_pk_mul_f32 v[184:185], v[30:31], v[148:149] op_sel_hi:[1,0]
	v_pk_mul_f32 v[188:189], v[28:29], v[148:149] op_sel_hi:[1,0]
	v_pk_mul_f32 v[192:193], v[26:27], v[148:149] op_sel_hi:[1,0]
	v_pk_mul_f32 v[194:195], v[24:25], v[148:149] op_sel_hi:[1,0]
	v_pk_mul_f32 v[196:197], v[22:23], v[148:149] op_sel_hi:[1,0]
	v_pk_mul_f32 v[198:199], v[20:21], v[148:149] op_sel_hi:[1,0]
	s_cbranch_vccnz .LBB0_213
	v_pk_mul_f32 v[148:149], v[186:187], v[186:187]
	v_pk_mul_f32 v[150:151], v[190:191], v[190:191]
	v_mov_b32_e32 v153, v149
	v_mov_b32_e32 v152, v150
	v_pk_mov_b32 v[148:149], v[150:151], v[148:149] op_sel:[1,0]
	v_pk_mul_f32 v[150:151], v[184:185], v[184:185]
	v_pk_add_f32 v[148:149], v[148:149], v[152:153]
	v_pk_mul_f32 v[152:153], v[188:189], v[188:189]
	v_pk_add_f32 v[148:149], v[148:149], v[148:149] op_sel_hi:[0,1]
	v_mov_b32_e32 v154, v152
	v_mov_b32_e32 v155, v151
	v_pk_mov_b32 v[150:151], v[152:153], v[150:151] op_sel:[1,0]
	v_mul_f32_e32 v148, v194, v194
	v_pk_add_f32 v[150:151], v[150:151], v[154:155]
	v_pk_fma_f32 v[152:153], v[194:195], v[194:195], v[148:149] op_sel_hi:[1,1,0]
	v_mul_f32_e32 v148, v192, v192
	v_pk_add_f32 v[150:151], v[150:151], v[150:151] op_sel_hi:[0,1]
	v_pk_fma_f32 v[154:155], v[192:193], v[192:193], v[148:149] op_sel_hi:[1,1,0]
	v_mul_f32_e32 v152, v198, v198
	v_mul_f32_e32 v154, v199, v199
	v_mul_f32_e32 v148, v196, v196
	v_mul_f32_e32 v150, v197, v197
	v_pk_add_f32 v[152:153], v[152:153], v[154:155]
	v_pk_add_f32 v[148:149], v[148:149], v[150:151]
	v_and_b32_e32 v150, 64, v204
	v_pk_add_f32 v[148:149], v[152:153], v[148:149]
	v_add_u32_e32 v150, 64, v150
	v_add_f32_e32 v148, v148, v149
	v_xor_b32_e32 v149, 16, v204
	v_cmp_lt_i32_e32 vcc, v149, v150
	v_mov_b32_e32 v183, v2
	v_lshl_add_u64 v[152:153], v[162:163], 0, v[182:183]
	v_cndmask_b32_e32 v149, v204, v149, vcc
	v_lshlrev_b32_e32 v149, 2, v149
	ds_bpermute_b32 v149, v149, v148
	global_load_dwordx4 v[152:155], v[152:153], off
	s_mov_b32 s28, s64
	s_mov_b32 s29, s64
	s_waitcnt lgkmcnt(0)
	v_add_f32_e32 v148, v148, v149
	v_xor_b32_e32 v149, 32, v204
	v_cmp_lt_i32_e32 vcc, v149, v150
	s_nop 1
	v_cndmask_b32_e32 v149, v204, v149, vcc
	v_lshlrev_b32_e32 v149, 2, v149
	ds_bpermute_b32 v149, v149, v148
	s_waitcnt lgkmcnt(0)
	v_add_f32_e32 v148, v148, v149
	v_fmamk_f32 v148, v148, 0x3c800000, v202
	v_rsq_f32_e32 v200, v148
	v_lshl_add_u64 v[148:149], v[160:161], 0, v[182:183]
	global_load_dwordx4 v[148:151], v[148:149], off
	global_load_dwordx4 v[218:221], v[164:165], off offset:2048
	global_load_dwordx4 v[222:225], v[166:167], off offset:2048
	v_pk_mul_f32 v[186:187], v[186:187], v[200:201] op_sel_hi:[1,0]
	s_nop 0
	v_pk_mul_f32 v[206:207], v[146:147], v[186:187]
	v_pk_mul_f32 v[184:185], v[184:185], v[200:201] op_sel_hi:[1,0]
	v_pk_mul_f32 v[186:187], v[188:189], v[200:201] op_sel_hi:[1,0]
	v_pk_mul_f32 v[190:191], v[190:191], v[200:201] op_sel_hi:[1,0]
	v_pk_mul_f32 v[188:189], v[140:141], v[186:187]
	v_pk_mul_f32 v[184:185], v[142:143], v[184:185]
	v_pk_mul_f32 v[208:209], v[144:145], v[190:191]
	v_pk_mul_f32 v[194:195], v[194:195], v[200:201] op_sel_hi:[1,0]
	v_pk_mul_f32 v[192:193], v[192:193], v[200:201] op_sel_hi:[1,0]
	s_waitcnt vmcnt(3)
	v_pk_mul_f32 v[186:187], v[154:155], v[184:185]
	v_pk_mul_f32 v[190:191], v[152:153], v[188:189]
	s_waitcnt vmcnt(2)
	v_pk_fma_f32 v[186:187], v[150:151], v[206:207], v[186:187] neg_lo:[0,0,1] neg_hi:[0,0,1]
	v_pk_fma_f32 v[190:191], v[148:149], v[208:209], v[190:191] neg_lo:[0,0,1] neg_hi:[0,0,1]
	v_pk_mul_f32 v[150:151], v[150:151], v[184:185]
	v_pk_mul_f32 v[148:149], v[148:149], v[188:189]
	v_pk_fma_f32 v[150:151], v[154:155], v[206:207], v[150:151]
	v_pk_fma_f32 v[148:149], v[152:153], v[208:209], v[148:149]
	v_pk_mul_f32 v[184:185], s[28:29], v[150:151]
	v_pk_mul_f32 v[188:189], s[64:65], v[148:149]
	s_nop 0
	v_pk_mul_f32 v[206:207], v[138:139], v[192:193]
	v_pk_mul_f32 v[208:209], v[136:137], v[194:195]
	v_pk_mul_f32 v[192:193], v[196:197], v[200:201] op_sel_hi:[1,0]
	v_pk_mul_f32 v[194:195], v[198:199], v[200:201] op_sel_hi:[1,0]
	v_pk_mul_f32 v[198:199], v[134:135], v[192:193]
	v_pk_mul_f32 v[196:197], v[132:133], v[194:195]
	v_pk_mul_f32 v[186:187], s[28:29], v[186:187]
	v_pk_mul_f32 v[190:191], s[64:65], v[190:191]
	s_waitcnt vmcnt(0)
	v_pk_mul_f32 v[192:193], v[224:225], v[198:199]
	v_pk_mul_f32 v[194:195], v[222:223], v[196:197]
	v_pk_fma_f32 v[192:193], v[220:221], v[206:207], v[192:193] neg_lo:[0,0,1] neg_hi:[0,0,1]
	v_pk_fma_f32 v[194:195], v[218:219], v[208:209], v[194:195] neg_lo:[0,0,1] neg_hi:[0,0,1]
	v_pk_mul_f32 v[150:151], v[220:221], v[198:199]
	v_pk_mul_f32 v[148:149], v[218:219], v[196:197]
	v_pk_fma_f32 v[150:151], v[224:225], v[206:207], v[150:151]
	v_pk_fma_f32 v[148:149], v[222:223], v[208:209], v[148:149]
	v_pk_mul_f32 v[192:193], s[28:29], v[192:193]
	v_pk_mul_f32 v[194:195], s[64:65], v[194:195]
	v_pk_mul_f32 v[196:197], s[28:29], v[150:151]
	v_pk_mul_f32 v[198:199], s[64:65], v[148:149]
.LBB0_213:
	v_add_u32_e32 v148, 0xa0, v172
	v_mad_i64_i32 v[148:149], s[24:25], s62, v148, 0
	v_lshl_add_u64 v[148:149], v[148:149], 1, v[180:181]
	v_cvt_pk_bf16_f32 v150, v190, v191
	v_cvt_pk_bf16_f32 v151, v186, v187
	global_store_dwordx2 v[148:149], v[150:151], off
	v_cvt_pk_bf16_f32 v150, v188, v189
	v_cvt_pk_bf16_f32 v151, v184, v185
	global_store_dwordx2 v[148:149], v[150:151], off offset:32
	v_cvt_pk_bf16_f32 v150, v194, v195
	v_cvt_pk_bf16_f32 v151, v192, v193
	global_store_dwordx2 v[148:149], v[150:151], off offset:64
	v_cvt_pk_bf16_f32 v150, v198, v199
	v_cvt_pk_bf16_f32 v151, v196, v197
	global_store_dwordx2 v[148:149], v[150:151], off offset:96
	s_nop 0
	s_and_b64 vcc, exec, s[40:41]
	s_nop 1
	v_fmamk_f32 v148, v217, 0x3a800000, v202
	v_rsq_f32_e32 v188, v148
	s_nop 0
	v_pk_mul_f32 v[150:151], v[18:19], v[188:189] op_sel_hi:[1,0]
	v_pk_mul_f32 v[154:155], v[16:17], v[188:189] op_sel_hi:[1,0]
	v_pk_mul_f32 v[148:149], v[14:15], v[188:189] op_sel_hi:[1,0]
	v_pk_mul_f32 v[152:153], v[12:13], v[188:189] op_sel_hi:[1,0]
	v_pk_mul_f32 v[174:175], v[10:11], v[188:189] op_sel_hi:[1,0]
	v_pk_mul_f32 v[184:185], v[8:9], v[188:189] op_sel_hi:[1,0]
	v_pk_mul_f32 v[186:187], v[6:7], v[188:189] op_sel_hi:[1,0]
	v_pk_mul_f32 v[188:189], v[4:5], v[188:189] op_sel_hi:[1,0]
	s_cbranch_vccnz .LBB0_215
	v_pk_mul_f32 v[190:191], v[150:151], v[150:151]
	v_pk_mul_f32 v[192:193], v[154:155], v[154:155]
	v_mov_b32_e32 v195, v191
	v_mov_b32_e32 v194, v192
	v_pk_mov_b32 v[190:191], v[192:193], v[190:191] op_sel:[1,0]
	v_pk_mul_f32 v[192:193], v[148:149], v[148:149]
	v_pk_add_f32 v[190:191], v[190:191], v[194:195]
	v_pk_mul_f32 v[194:195], v[152:153], v[152:153]
	v_pk_add_f32 v[190:191], v[190:191], v[190:191] op_sel_hi:[0,1]
	v_mov_b32_e32 v196, v194
	v_mov_b32_e32 v197, v193
	v_pk_mov_b32 v[192:193], v[194:195], v[192:193] op_sel:[1,0]
	v_mul_f32_e32 v190, v184, v184
	v_pk_add_f32 v[192:193], v[192:193], v[196:197]
	v_pk_fma_f32 v[194:195], v[184:185], v[184:185], v[190:191] op_sel_hi:[1,1,0]
	v_mul_f32_e32 v190, v174, v174
	v_pk_add_f32 v[192:193], v[192:193], v[192:193] op_sel_hi:[0,1]
	v_pk_fma_f32 v[196:197], v[174:175], v[174:175], v[190:191] op_sel_hi:[1,1,0]
	v_mul_f32_e32 v194, v188, v188
	v_mul_f32_e32 v196, v189, v189
	v_mul_f32_e32 v190, v186, v186
	v_mul_f32_e32 v192, v187, v187
	v_pk_add_f32 v[194:195], v[194:195], v[196:197]
	v_pk_add_f32 v[190:191], v[190:191], v[192:193]
	v_xor_b32_e32 v183, 16, v204
	v_pk_add_f32 v[190:191], v[194:195], v[190:191]
	s_mov_b32 s28, s64
	v_add_f32_e32 v173, v190, v191
	v_and_b32_e32 v190, 64, v204
	v_add_u32_e32 v190, 64, v190
	v_cmp_lt_i32_e32 vcc, v183, v190
	s_mov_b32 s29, s64
	s_nop 0
	v_cndmask_b32_e32 v183, v204, v183, vcc
	v_lshlrev_b32_e32 v183, 2, v183
	ds_bpermute_b32 v183, v183, v173
	s_waitcnt lgkmcnt(0)
	v_add_f32_e32 v173, v173, v183
	v_xor_b32_e32 v183, 32, v204
	v_cmp_lt_i32_e32 vcc, v183, v190
	s_nop 1
	v_cndmask_b32_e32 v183, v204, v183, vcc
	v_lshlrev_b32_e32 v183, 2, v183
	ds_bpermute_b32 v183, v183, v173
	s_waitcnt lgkmcnt(0)
	v_add_f32_e32 v173, v173, v183
	v_mov_b32_e32 v183, v2
	v_lshl_add_u64 v[192:193], v[160:161], 0, v[182:183]
	v_lshl_add_u64 v[182:183], v[162:163], 0, v[182:183]
	global_load_dwordx4 v[192:195], v[192:193], off
	v_fmamk_f32 v173, v173, 0x3c800000, v202
	global_load_dwordx4 v[196:199], v[182:183], off
	global_load_dwordx4 v[218:221], v[164:165], off offset:3072
	global_load_dwordx4 v[222:225], v[166:167], off offset:3072
	v_rsq_f32_e32 v190, v173
	s_nop 0
	v_pk_mul_f32 v[150:151], v[150:151], v[190:191] op_sel_hi:[1,0]
	s_nop 0
	v_pk_mul_f32 v[146:147], v[146:147], v[150:151]
	v_pk_mul_f32 v[148:149], v[148:149], v[190:191] op_sel_hi:[1,0]
	v_pk_mul_f32 v[150:151], v[152:153], v[190:191] op_sel_hi:[1,0]
	v_pk_mul_f32 v[154:155], v[154:155], v[190:191] op_sel_hi:[1,0]
	v_pk_mul_f32 v[140:141], v[140:141], v[150:151]
	v_pk_mul_f32 v[142:143], v[142:143], v[148:149]
	v_pk_mul_f32 v[144:145], v[144:145], v[154:155]
	v_pk_mul_f32 v[182:183], v[184:185], v[190:191] op_sel_hi:[1,0]
	v_pk_mul_f32 v[174:175], v[174:175], v[190:191] op_sel_hi:[1,0]
	v_pk_mul_f32 v[136:137], v[136:137], v[182:183]
	v_pk_mul_f32 v[138:139], v[138:139], v[174:175]
	v_pk_mul_f32 v[174:175], v[186:187], v[190:191] op_sel_hi:[1,0]
	v_pk_mul_f32 v[182:183], v[188:189], v[190:191] op_sel_hi:[1,0]
	v_pk_mul_f32 v[134:135], v[134:135], v[174:175]
	v_pk_mul_f32 v[132:133], v[132:133], v[182:183]
	s_waitcnt vmcnt(2)
	v_pk_mul_f32 v[148:149], v[198:199], v[142:143]
	v_pk_mul_f32 v[150:151], v[196:197], v[140:141]
	v_pk_mul_f32 v[142:143], v[194:195], v[142:143]
	v_pk_mul_f32 v[140:141], v[192:193], v[140:141]
	v_pk_fma_f32 v[152:153], v[192:193], v[144:145], v[150:151] neg_lo:[0,0,1] neg_hi:[0,0,1]
	v_pk_fma_f32 v[148:149], v[194:195], v[146:147], v[148:149] neg_lo:[0,0,1] neg_hi:[0,0,1]
	v_pk_fma_f32 v[140:141], v[196:197], v[144:145], v[140:141]
	v_pk_fma_f32 v[142:143], v[198:199], v[146:147], v[142:143]
	v_pk_mul_f32 v[150:151], s[28:29], v[148:149]
	v_pk_mul_f32 v[154:155], s[64:65], v[152:153]
	v_pk_mul_f32 v[148:149], s[28:29], v[142:143]
	v_pk_mul_f32 v[152:153], s[64:65], v[140:141]
	s_nop 0
	s_waitcnt vmcnt(0)
	v_pk_mul_f32 v[174:175], v[224:225], v[134:135]
	v_pk_mul_f32 v[182:183], v[222:223], v[132:133]
	v_pk_mul_f32 v[134:135], v[220:221], v[134:135]
	v_pk_mul_f32 v[132:133], v[218:219], v[132:133]
	v_pk_fma_f32 v[182:183], v[218:219], v[136:137], v[182:183] neg_lo:[0,0,1] neg_hi:[0,0,1]
	v_pk_fma_f32 v[174:175], v[220:221], v[138:139], v[174:175] neg_lo:[0,0,1] neg_hi:[0,0,1]
	v_pk_fma_f32 v[132:133], v[222:223], v[136:137], v[132:133]
	v_pk_fma_f32 v[134:135], v[224:225], v[138:139], v[134:135]
	v_pk_mul_f32 v[174:175], s[28:29], v[174:175]
	v_pk_mul_f32 v[184:185], s[64:65], v[182:183]
	v_pk_mul_f32 v[186:187], s[28:29], v[134:135]
	v_pk_mul_f32 v[188:189], s[64:65], v[132:133]
